# combo7 + attention softmax/P.V block software-pipelined inside the wave: V-fragment LDS reads issued one group ahead, exps of keys 32-63 and packing/row sums interleaved with the P.V MFMAs
# speedup vs baseline: 1.0108x; 1.0012x over previous
; #define LAS __attribute__((address_space(3)))
; __device__ __forceinline__ unsigned cvt_pk_bf16(float lo, float hi) { unsigned r; asm volatile("v_cvt_pk_bf16_f32 %0, %1, %2" : "=v"(r) : "v"(lo), "v"(hi)); return r; }
; __device__ __forceinline__ float fast_exp2(float x) { return __builtin_amdgcn_exp2f(x); }
; __device__ __forceinline__ void attn_unit(LAS unsigned char* lds, const bf16* UA, bf16* Y, int bl, int h, int qb,
;                                           const float* qkg, const float* rel_bias, const float* lamv, const float* dgain, float lam_init, int tid, int wave, int lane) {
;     ...
;             u32x4 P[2][2];
; #pragma unroll
;             for (int kb = 0; kb < 4; ++kb)
; #pragma unroll
;                 for (int qb2 = 0; qb2 < 2; ++qb2) {
; #pragma unroll
;                     for (int i = 0; i < 4; ++i) { S[kb][qb2][i] = fast_exp2(S[kb][qb2][i]); lsum[qb2] += S[kb][qb2][i]; }
;                     const unsigned w0 = cvt_pk_bf16(S[kb][qb2][0], S[kb][qb2][1]), w1 = cvt_pk_bf16(S[kb][qb2][2], S[kb][qb2][3]);
;                     if (kb & 1) { P[kb >> 1][qb2].z = w0; P[kb >> 1][qb2].w = w1; } else { P[kb >> 1][qb2].x = w0; P[kb >> 1][qb2].y = w1; }
;                 }
; #pragma unroll
;             for (int s2 = 0; s2 < 2; ++s2) {
; #pragma unroll
;                 for (int dq = 0; dq < 2; ++dq) {
;                     bf16x8 vf[4];
; #pragma unroll
;                     for (int e = 0; e < 4; ++e) { const LAS unsigned char* vp = Vb + voff + (32 * s2) * AT_VROW + (16 * (4 * dq + e)) * 2;
;                         const s16x4 lo = __builtin_bit_cast(s16x4, __builtin_amdgcn_ds_read_tr16_b64_v4i16((LAS v4i16_t*)vp)), hi4 = __builtin_bit_cast(s16x4, __builtin_amdgcn_ds_read_tr16_b64_v4i16((LAS v4i16_t*)(vp + 16 * AT_VROW)));
;                         vf[e] = (bf16x8){lo[0], lo[1], lo[2], lo[3], hi4[0], hi4[1], hi4[2], hi4[3]}; }
;                     __builtin_amdgcn_s_setprio(1);
; #pragma unroll
;                     for (int e = 0; e < 4; ++e)
; #pragma unroll
;                         for (int qb2 = 0; qb2 < 2; ++qb2) O[4 * dq + e][qb2] = __builtin_amdgcn_mfma_f32_16x16x32_bf16(vf[e], __builtin_bit_cast(bf16x8, P[s2][qb2]), O[4 * dq + e][qb2], 0, 0, 0);
;                     __builtin_amdgcn_s_setprio(0);
;                     __builtin_amdgcn_sched_barrier(0);
;                 }
;             }
.LBB0_523:
	v_add_u32_e32 v188, s44, v145
	ds_read_b64_tr_b16 v[232:233], v188 offset:36864
	ds_read_b64_tr_b16 v[236:237], v188 offset:36896
	ds_read_b64_tr_b16 v[240:241], v188 offset:36928
	ds_read_b64_tr_b16 v[244:245], v188 offset:36960
	ds_read_b64_tr_b16 v[234:235], v188 offset:41472
	ds_read_b64_tr_b16 v[238:239], v188 offset:41504
	ds_read_b64_tr_b16 v[242:243], v188 offset:41536
	ds_read_b64_tr_b16 v[246:247], v188 offset:41568
	v_exp_f32_e32 v153, v128
	v_exp_f32_e32 v152, v124
	v_exp_f32_e32 v155, v129
	v_exp_f32_e32 v154, v125
	v_exp_f32_e32 v157, v130
	v_exp_f32_e32 v156, v126
	v_exp_f32_e32 v159, v131
	v_exp_f32_e32 v158, v127
	v_exp_f32_e32 v161, v120
	v_pk_add_f32 v[132:133], v[152:153], v[132:133]
	v_exp_f32_e32 v160, v116
	v_cvt_pk_bf16_f32 v128, v153, v155
	v_exp_f32_e32 v163, v121
	v_pk_add_f32 v[132:133], v[154:155], v[132:133]
	v_exp_f32_e32 v162, v117
	v_cvt_pk_bf16_f32 v129, v157, v159
	v_exp_f32_e32 v165, v122
	v_pk_add_f32 v[132:133], v[156:157], v[132:133]
	v_exp_f32_e32 v164, v118
	v_cvt_pk_bf16_f32 v124, v152, v154
	v_exp_f32_e32 v167, v123
	v_pk_add_f32 v[132:133], v[158:159], v[132:133]
	v_exp_f32_e32 v166, v119
	v_cvt_pk_bf16_f32 v125, v156, v158
	v_cvt_pk_bf16_f32 v130, v161, v163
	v_cvt_pk_bf16_f32 v126, v160, v162
	v_cvt_pk_bf16_f32 v131, v165, v167
	v_cvt_pk_bf16_f32 v127, v164, v166
	s_waitcnt lgkmcnt(0)
	ds_read_b64_tr_b16 v[200:201], v188 offset:36992
	ds_read_b64_tr_b16 v[204:205], v188 offset:37024
	ds_read_b64_tr_b16 v[208:209], v188 offset:37056
	ds_read_b64_tr_b16 v[248:249], v188 offset:37088
	ds_read_b64_tr_b16 v[202:203], v188 offset:41600
	ds_read_b64_tr_b16 v[206:207], v188 offset:41632
	ds_read_b64_tr_b16 v[210:211], v188 offset:41664
	ds_read_b64_tr_b16 v[250:251], v188 offset:41696
	s_setprio 1
	v_mfma_f32_16x16x32_bf16 v[60:63], v[232:235], v[128:131], v[60:63]
	v_exp_f32_e32 v153, v112
	v_mfma_f32_16x16x32_bf16 v[56:59], v[232:235], v[124:127], v[56:59]
	v_exp_f32_e32 v152, v108
	v_mfma_f32_16x16x32_bf16 v[52:55], v[236:239], v[128:131], v[52:55]
	v_exp_f32_e32 v155, v113
	v_mfma_f32_16x16x32_bf16 v[48:51], v[236:239], v[124:127], v[48:51]
	v_exp_f32_e32 v154, v109
	v_mfma_f32_16x16x32_bf16 v[44:47], v[240:243], v[128:131], v[44:47]
	v_exp_f32_e32 v157, v114
	v_mfma_f32_16x16x32_bf16 v[36:39], v[240:243], v[124:127], v[36:39]
	v_exp_f32_e32 v156, v110
	v_mfma_f32_16x16x32_bf16 v[40:43], v[244:247], v[128:131], v[40:43]
	v_exp_f32_e32 v159, v115
	v_mfma_f32_16x16x32_bf16 v[24:27], v[244:247], v[124:127], v[24:27]
	v_exp_f32_e32 v158, v111
	s_waitcnt lgkmcnt(0)
	ds_read_b64_tr_b16 v[232:233], v188 offset:46080
	ds_read_b64_tr_b16 v[236:237], v188 offset:46112
	ds_read_b64_tr_b16 v[240:241], v188 offset:46144
	ds_read_b64_tr_b16 v[244:245], v188 offset:46176
	ds_read_b64_tr_b16 v[234:235], v188 offset:50688
	ds_read_b64_tr_b16 v[238:239], v188 offset:50720
	ds_read_b64_tr_b16 v[242:243], v188 offset:50752
	ds_read_b64_tr_b16 v[246:247], v188 offset:50784
	v_mfma_f32_16x16x32_bf16 v[32:35], v[200:203], v[128:131], v[32:35]
	v_exp_f32_e32 v193, v104
	v_mfma_f32_16x16x32_bf16 v[20:23], v[200:203], v[124:127], v[20:23]
	v_exp_f32_e32 v192, v100
	v_cvt_pk_bf16_f32 v112, v153, v155
	v_mfma_f32_16x16x32_bf16 v[28:31], v[204:207], v[128:131], v[28:31]
	v_exp_f32_e32 v195, v105
	v_mfma_f32_16x16x32_bf16 v[8:11], v[204:207], v[124:127], v[8:11]
	v_exp_f32_e32 v194, v101
	v_cvt_pk_bf16_f32 v113, v157, v159
	v_mfma_f32_16x16x32_bf16 v[4:7], v[208:211], v[128:131], v[4:7]
	v_exp_f32_e32 v197, v106
	v_mfma_f32_16x16x32_bf16 v[0:3], v[208:211], v[124:127], v[0:3]
	v_exp_f32_e32 v196, v102
	v_cvt_pk_bf16_f32 v108, v152, v154
	v_mfma_f32_16x16x32_bf16 v[16:19], v[248:251], v[128:131], v[16:19]
	v_exp_f32_e32 v199, v107
	v_mfma_f32_16x16x32_bf16 v[12:15], v[248:251], v[124:127], v[12:15]
	v_exp_f32_e32 v198, v103
	v_cvt_pk_bf16_f32 v109, v156, v158
	v_cvt_pk_bf16_f32 v114, v193, v195
	v_cvt_pk_bf16_f32 v110, v192, v194
	v_cvt_pk_bf16_f32 v115, v197, v199
	v_cvt_pk_bf16_f32 v111, v196, v198
	s_waitcnt lgkmcnt(0)
	ds_read_b64_tr_b16 v[200:201], v188 offset:46208
	ds_read_b64_tr_b16 v[204:205], v188 offset:46240
	ds_read_b64_tr_b16 v[208:209], v188 offset:46272
	ds_read_b64_tr_b16 v[248:249], v188 offset:46304
	ds_read_b64_tr_b16 v[202:203], v188 offset:50816
	ds_read_b64_tr_b16 v[206:207], v188 offset:50848
	ds_read_b64_tr_b16 v[210:211], v188 offset:50880
	ds_read_b64_tr_b16 v[250:251], v188 offset:50912
	v_mfma_f32_16x16x32_bf16 v[60:63], v[232:235], v[112:115], v[60:63]
	v_pk_add_f32 v[132:133], v[160:161], v[132:133]
	v_mfma_f32_16x16x32_bf16 v[56:59], v[232:235], v[108:111], v[56:59]
	v_pk_add_f32 v[132:133], v[162:163], v[132:133]
	v_mfma_f32_16x16x32_bf16 v[52:55], v[236:239], v[112:115], v[52:55]
	v_pk_add_f32 v[132:133], v[164:165], v[132:133]
	v_mfma_f32_16x16x32_bf16 v[48:51], v[236:239], v[108:111], v[48:51]
	v_pk_add_f32 v[132:133], v[166:167], v[132:133]
	v_mfma_f32_16x16x32_bf16 v[44:47], v[240:243], v[112:115], v[44:47]
	v_pk_add_f32 v[132:133], v[152:153], v[132:133]
	v_mfma_f32_16x16x32_bf16 v[36:39], v[240:243], v[108:111], v[36:39]
	v_pk_add_f32 v[132:133], v[154:155], v[132:133]
	v_mfma_f32_16x16x32_bf16 v[40:43], v[244:247], v[112:115], v[40:43]
	v_pk_add_f32 v[132:133], v[156:157], v[132:133]
	v_mfma_f32_16x16x32_bf16 v[24:27], v[244:247], v[108:111], v[24:27]
	v_pk_add_f32 v[132:133], v[158:159], v[132:133]
	s_waitcnt lgkmcnt(3)
	v_mfma_f32_16x16x32_bf16 v[32:35], v[200:203], v[112:115], v[32:35]
	v_mfma_f32_16x16x32_bf16 v[20:23], v[200:203], v[108:111], v[20:23]
	v_pk_add_f32 v[132:133], v[192:193], v[132:133]
	s_waitcnt lgkmcnt(2)
	v_mfma_f32_16x16x32_bf16 v[28:31], v[204:207], v[112:115], v[28:31]
	v_mfma_f32_16x16x32_bf16 v[8:11], v[204:207], v[108:111], v[8:11]
	v_pk_add_f32 v[132:133], v[194:195], v[132:133]
	s_waitcnt lgkmcnt(1)
	v_mfma_f32_16x16x32_bf16 v[4:7], v[208:211], v[112:115], v[4:7]
	v_mfma_f32_16x16x32_bf16 v[0:3], v[208:211], v[108:111], v[0:3]
	v_pk_add_f32 v[132:133], v[196:197], v[132:133]
	s_waitcnt lgkmcnt(0)
	v_mfma_f32_16x16x32_bf16 v[16:19], v[248:251], v[112:115], v[16:19]
	v_mfma_f32_16x16x32_bf16 v[12:15], v[248:251], v[108:111], v[12:15]
	v_pk_add_f32 v[132:133], v[198:199], v[132:133]
	s_setprio 0
